# final_norm_pass: lane owns columns 4*lane+256*j so every f32 output store instruction writes 1 KiB contiguous (was 16-B pieces at 64-B stride); X16 fragment-layout loads as 16 dwordx2
# speedup vs baseline: 1.0266x; 1.0045x over previous
; __device__ __forceinline__ int opaque_tid(int wave_s) { int l; asm volatile("v_mbcnt_lo_u32_b32 %0, -1, 0\n\tv_mbcnt_hi_u32_b32 %0, -1, %0" : "=v"(l)); return (wave_s << 6) | l; }
; __device__ __forceinline__ float bflo(unsigned w) { return __uint_as_float(w << 16); }
; __device__ __forceinline__ float bfhi(unsigned w) { return __uint_as_float(w & 0xffff0000u); }
; __device__ __forceinline__ void final_norm_pass(const bf16_t* x16, float* out, const float* nw, int vcu, int ngw, const int wave_s) {
;     const int tid_ = opaque_tid(wave_s), lane = tid_ & 63, gw = vcu * NWAVES + (tid_ >> 6);
;     f32x4 wv[4];
; #pragma unroll
;     for (int j = 0; j < 4; ++j) wv[j] = *(const f32x4*)(nw + 16 * lane + 4 * j);
;     for (int m0 = 4 * gw; m0 < MTOK; m0 += 4 * ngw) {
;         u32x4 a[4], b[4];
; #pragma unroll
;         for (int i = 0; i < 4; ++i) { const u32x4* xr = (const u32x4*)(x16 + (size_t)(m0 + i) * DM + 16 * lane); a[i] = xr[0]; b[i] = xr[1]; }
; #pragma unroll
;         for (int i = 0; i < 4; ++i) {
;             f32x4 v[4];
;             v[0] = (f32x4){bflo(a[i].x), bfhi(a[i].x), bflo(a[i].y), bfhi(a[i].y)}; v[1] = (f32x4){bflo(a[i].z), bfhi(a[i].z), bflo(a[i].w), bfhi(a[i].w)};
;             v[2] = (f32x4){bflo(b[i].x), bfhi(b[i].x), bflo(b[i].y), bfhi(b[i].y)}; v[3] = (f32x4){bflo(b[i].z), bfhi(b[i].z), bflo(b[i].w), bfhi(b[i].w)};
;             float s = 0.f;
; #pragma unroll
;             for (int j = 0; j < 4; ++j) s += (v[j].x * v[j].x + v[j].y * v[j].y) + (v[j].z * v[j].z + v[j].w * v[j].w);
;             const float rstd = 1.0f / sqrtf(wave_sum(s, lane) * (1.0f / DM) + EPS);
;             f32x4* orow = (f32x4*)(out + (size_t)(m0 + i) * DM + 16 * lane);
; #pragma unroll
;             for (int j = 0; j < 4; ++j) orow[j] = v[j] * rstd * wv[j];
;         }
;     }
; }
.LBB0_1351:
	v_readlane_b32 s7, v255, 4
	v_mbcnt_lo_u32_b32 v0, -1, 0
	v_mbcnt_hi_u32_b32 v0, -1, v0
	s_nop 1
	v_or_b32_e32 v1, s7, v0
	v_ashrrev_i32_e32 v1, 4, v1
	v_and_b32_e32 v1, -4, v1
	v_lshl_add_u32 v16, s6, 5, v1
	s_mov_b32 s6, 0x10000
	v_cmp_gt_i32_e32 vcc, s6, v16
	s_and_saveexec_b64 s[6:7], vcc
	s_cbranch_execz .LBB0_1354
	v_and_b32_e32 v22, 63, v0
	v_lshlrev_b32_e32 v20, 6, v22
	v_lshlrev_b32_e32 v166, 4, v22
	s_waitcnt lgkmcnt(0)
	global_load_dwordx4 v[0:3], v166, s[0:1] offset:3072
	global_load_dwordx4 v[4:7], v166, s[0:1] offset:2048
	global_load_dwordx4 v[8:11], v166, s[0:1] offset:1024
	global_load_dwordx4 v[12:15], v166, s[0:1]
	v_lshlrev_b32_e32 v17, 2, v22
	v_xor_b32_e32 v110, 4, v17
	v_xor_b32_e32 v111, 8, v17
	v_xor_b32_e32 v112, 16, v17
	v_xor_b32_e32 v113, 32, v17
	v_xor_b32_e32 v114, 64, v17
	v_xor_b32_e32 v115, 0x80, v17
	v_ashrrev_i32_e32 v17, 31, v16
	v_lshlrev_b64 v[18:19], 12, v[16:17]
	v_or_b32_e32 v18, v18, v166
	v_lshlrev_b64 v[20:21], 11, v[16:17]
	s_lshl_b32 s10, s38, 5
	v_lshl_add_u64 v[18:19], s[4:5], 0, v[18:19]
	s_mov_b64 s[0:1], 0x3c00
	v_lshl_or_b32 v20, v22, 5, v20
	v_lshl_add_u64 v[18:19], v[18:19], 0, s[0:1]
	s_ashr_i32 s11, s10, 31
	v_lshl_add_u64 v[20:21], s[2:3], 0, v[20:21]
	s_mov_b64 s[0:1], 0x8001810
	s_lshl_b64 s[12:13], s[10:11], 12
	v_lshl_add_u64 v[20:21], v[20:21], 0, s[0:1]
	s_lshl_b64 s[14:15], s[10:11], 11
	s_mov_b64 s[16:17], 0
	s_movk_i32 s11, 0xec00
	s_movk_i32 s18, 0xf000
	v_mov_b32_e32 v17, 0x358637bd
	s_mov_b32 s19, 0xf800000
	v_mov_b32_e32 v116, 0x260
	s_movk_i32 s20, 0xc400
	s_movk_i32 s21, 0xc800
	s_movk_i32 s22, 0xcc00
	s_movk_i32 s23, 0xd000
	s_movk_i32 s24, 0xd400
	s_movk_i32 s25, 0xd800
	s_movk_i32 s26, 0xdc00
	s_movk_i32 s27, 0xe000
	s_movk_i32 s28, 0xe400
	s_movk_i32 s29, 0xe800
	s_movk_i32 s30, 0xf400
	s_movk_i32 s31, 0xf800
	s_mov_b32 s33, 0xffff
	s_movk_i32 s34, 0xfc00
	s_mov_b64 s[36:37], 0x2000
	s_mov_b64 s[40:41], 0x4000
	s_mov_b64 s[42:43], 0x6000
	v_mbcnt_lo_u32_b32 v160, -1, 0
	v_mbcnt_hi_u32_b32 v160, -1, v160
	v_lshrrev_b32_e32 v161, 3, v160
	v_and_b32_e32 v163, 3, v161
	v_lshlrev_b32_e32 v162, 1, v163
	v_bfe_u32 v163, v161, 2, 1
	v_or_b32_e32 v162, v162, v163
	v_lshlrev_b32_e32 v162, 10, v162
	v_and_b32_e32 v163, 7, v160
	v_lshl_or_b32 v162, v163, 3, v162
	v_and_b32_e32 v163, 15, v16
	v_mul_u32_u24_e32 v163, 0x7c0, v163
	v_lshlrev_b32_e32 v161, 5, v160
	v_sub_u32_e32 v162, v162, v161
	v_sub_u32_e32 v162, v162, v163
	v_add_u32_e32 v162, 0xffffe7f0, v162
	v_ashrrev_i32_e32 v163, 31, v162
.LBB0_1353:
	v_lshl_add_u64 v[164:165], v[20:21], 0, v[162:163]
	v_lshl_add_u64 v[166:167], v[164:165], 0, s[36:37]
	v_lshl_add_u64 v[168:169], v[164:165], 0, s[40:41]
	v_lshl_add_u64 v[170:171], v[164:165], 0, s[42:43]
	v_add_co_u32_e32 v38, vcc, 0xffffe7f0, v20
	v_add_co_u32_e64 v40, s[0:1], -16, v20
	s_nop 0
	v_addc_co_u32_e32 v39, vcc, -1, v21, vcc
	v_addc_co_u32_e64 v41, s[0:1], -1, v21, s[0:1]
	global_load_dwordx2 v[64:65], v[168:169], off offset:192
	global_load_dwordx2 v[66:67], v[170:171], off offset:192
	global_load_dwordx2 v[58:59], v[164:165], off offset:192
	global_load_dwordx2 v[60:61], v[166:167], off offset:192
	v_add_co_u32_e32 v40, vcc, 0xffffe800, v20
	global_load_dwordx2 v[70:71], v[164:165], off
	global_load_dwordx2 v[72:73], v[166:167], off
	s_nop 0
	v_addc_co_u32_e32 v41, vcc, -1, v21, vcc
	v_add_co_u32_e32 v38, vcc, 0xffffeff0, v20
	global_load_dwordx2 v[78:79], v[168:169], off
	global_load_dwordx2 v[80:81], v[170:171], off
	s_nop 0
	v_addc_co_u32_e32 v39, vcc, -1, v21, vcc
	v_add_co_u32_e32 v40, vcc, 0xfffff000, v20
	global_load_dwordx2 v[90:91], v[164:165], off offset:64
	global_load_dwordx2 v[92:93], v[166:167], off offset:64
	s_nop 0
	v_addc_co_u32_e32 v41, vcc, -1, v21, vcc
	v_add_co_u32_e32 v38, vcc, 0xfffff7f0, v20
	global_load_dwordx2 v[96:97], v[168:169], off offset:64
	global_load_dwordx2 v[98:99], v[170:171], off offset:64
	s_nop 0
	v_addc_co_u32_e32 v39, vcc, -1, v21, vcc
	v_add_co_u32_e32 v40, vcc, 0xfffff800, v20
	v_add_co_u32_e64 v22, s[0:1], s20, v18
	s_nop 0
	v_addc_co_u32_e32 v41, vcc, -1, v21, vcc
	global_load_dwordx2 v[100:101], v[164:165], off offset:128
	global_load_dwordx2 v[102:103], v[166:167], off offset:128
	global_load_dwordx2 v[118:119], v[168:169], off offset:128
	global_load_dwordx2 v[120:121], v[170:171], off offset:128
	v_addc_co_u32_e64 v23, s[0:1], -1, v19, s[0:1]
	v_add_co_u32_e64 v24, s[0:1], s21, v18
	v_add_u32_e32 v16, s10, v16
	s_nop 0
	v_addc_co_u32_e64 v25, s[0:1], -1, v19, s[0:1]
	v_add_co_u32_e64 v26, s[0:1], s22, v18
	v_lshl_add_u64 v[20:21], v[20:21], 0, s[14:15]
	s_nop 0
	v_addc_co_u32_e64 v27, s[0:1], -1, v19, s[0:1]
	v_add_co_u32_e64 v28, s[0:1], s23, v18
	s_waitcnt vmcnt(0) lgkmcnt(0)
; __device__ __forceinline__ float bflo(unsigned w) { return __uint_as_float(w << 16); }
; __device__ __forceinline__ float bfhi(unsigned w) { return __uint_as_float(w & 0xffff0000u); }
; __device__ __forceinline__ void final_norm_pass(const bf16_t* x16, float* out, const float* nw, int vcu, int ngw, const int wave_s) {
;     ...
;         for (int i = 0; i < 4; ++i) {
;             f32x4 v[4];
;             v[0] = (f32x4){bflo(a[i].x), bfhi(a[i].x), bflo(a[i].y), bfhi(a[i].y)}; v[1] = (f32x4){bflo(a[i].z), bfhi(a[i].z), bflo(a[i].w), bfhi(a[i].w)};
;             v[2] = (f32x4){bflo(b[i].x), bfhi(b[i].x), bflo(b[i].y), bfhi(b[i].y)}; v[3] = (f32x4){bflo(b[i].z), bfhi(b[i].z), bflo(b[i].w), bfhi(b[i].w)};
;             float s = 0.f;
; #pragma unroll
;             for (int j = 0; j < 4; ++j) s += (v[j].x * v[j].x + v[j].y * v[j].y) + (v[j].z * v[j].z + v[j].w * v[j].w);
	v_lshlrev_b32_e32 v62, 16, v64
	v_lshlrev_b32_e32 v56, 16, v58
	v_and_b32_e32 v57, 0xffff0000, v58
	v_lshlrev_b32_e32 v58, 16, v59
	v_lshlrev_b32_e32 v68, 16, v70
	v_and_b32_e32 v69, 0xffff0000, v70
	v_lshlrev_b32_e32 v70, 16, v71
	v_lshlrev_b32_e32 v83, 16, v61
	v_lshlrev_b32_e32 v82, 16, v60
	v_and_b32_e32 v61, 0xffff0000, v61
	v_and_b32_e32 v60, 0xffff0000, v60
	v_and_b32_e32 v63, 0xffff0000, v64
	v_lshlrev_b32_e32 v64, 16, v65
	v_and_b32_e32 v71, 0xffff0000, v71
	v_lshlrev_b32_e32 v95, 16, v73
	v_lshlrev_b32_e32 v94, 16, v72
	v_and_b32_e32 v73, 0xffff0000, v73
	v_and_b32_e32 v72, 0xffff0000, v72
	v_lshlrev_b32_e32 v74, 16, v80
	v_and_b32_e32 v135, 0xffff0000, v80
	v_mul_f32_e32 v80, v68, v68
	v_mul_f32_e32 v128, v70, v70
	v_and_b32_e32 v59, 0xffff0000, v59
	v_and_b32_e32 v65, 0xffff0000, v65
	v_mul_f32_e32 v104, v56, v56
	v_mul_f32_e32 v106, v58, v58
	v_pk_mul_f32 v[108:109], v[60:61], v[60:61]
	v_mul_f32_e32 v122, v62, v62
	v_mul_f32_e32 v124, v64, v64
	v_pk_mul_f32 v[130:131], v[72:73], v[72:73]
	v_lshlrev_b32_e32 v84, 16, v78
	v_lshlrev_b32_e32 v86, 16, v79
	v_pk_fma_f32 v[132:133], v[68:69], v[68:69], v[80:81] op_sel_hi:[1,1,0]
	v_pk_fma_f32 v[128:129], v[70:71], v[70:71], v[128:129] op_sel_hi:[1,1,0]
	v_lshlrev_b32_e32 v38, 16, v66
	v_lshlrev_b32_e32 v40, 16, v67
	v_and_b32_e32 v41, 0xffff0000, v67
	v_and_b32_e32 v85, 0xffff0000, v78
	v_and_b32_e32 v87, 0xffff0000, v79
	v_mov_b32_e32 v88, v94
	v_mov_b32_e32 v89, v72
	v_mov_b32_e32 v72, v95
	v_pk_fma_f32 v[104:105], v[56:57], v[56:57], v[104:105] op_sel_hi:[1,1,0]
	v_pk_fma_f32 v[106:107], v[58:59], v[58:59], v[106:107] op_sel_hi:[1,1,0]
	v_pk_fma_f32 v[108:109], v[82:83], v[82:83], v[108:109]
	v_pk_fma_f32 v[122:123], v[62:63], v[62:63], v[122:123] op_sel_hi:[1,1,0]
	v_pk_fma_f32 v[124:125], v[64:65], v[64:65], v[124:125] op_sel_hi:[1,1,0]
	v_pk_fma_f32 v[94:95], v[94:95], v[94:95], v[130:131]
	v_mul_f32_e32 v130, v84, v84
	v_mul_f32_e32 v134, v86, v86
	v_lshlrev_b32_e32 v78, 16, v90
	v_lshlrev_b32_e32 v80, 16, v91
	v_mov_b32_e32 v137, v129
	v_pk_add_f32 v[128:129], v[132:133], v[128:129]
	v_mov_b32_e32 v126, v38
	v_lshlrev_b32_e32 v76, 16, v81
	v_and_b32_e32 v77, 0xffff0000, v81
	v_mov_b32_e32 v136, v74
	v_and_b32_e32 v79, 0xffff0000, v90
	v_and_b32_e32 v81, 0xffff0000, v91
	v_pk_add_f32 v[140:141], v[108:109], v[108:109] op_sel_hi:[0,1]
	v_mul_f32_e32 v122, v40, v40
	v_mul_f32_e32 v124, v41, v41
	v_mov_b32_e32 v39, v105
	v_mov_b32_e32 v127, v107
	v_pk_add_f32 v[90:91], v[104:105], v[106:107]
	v_pk_add_f32 v[142:143], v[94:95], v[94:95] op_sel_hi:[0,1]
	v_pk_fma_f32 v[106:107], v[84:85], v[84:85], v[130:131] op_sel_hi:[1,1,0]
	v_pk_fma_f32 v[108:109], v[86:87], v[86:87], v[134:135] op_sel_hi:[1,1,0]
	v_mov_b32_e32 v75, v133
	v_mul_f32_e32 v128, v78, v78
	v_mul_f32_e32 v130, v80, v80
	v_and_b32_e32 v117, 0xffff0000, v66
	v_mov_b32_e32 v66, v82
	v_mov_b32_e32 v67, v60
	v_mov_b32_e32 v60, v83
	v_and_b32_e32 v83, 0xffff0000, v93
	v_and_b32_e32 v82, 0xffff0000, v92
	v_lshlrev_b32_e32 v90, 16, v98
	v_and_b32_e32 v154, 0xffff0000, v98
	v_lshlrev_b32_e32 v94, 16, v96
	v_lshlrev_b32_e32 v98, 16, v97
	v_pk_mul_f32 v[126:127], v[38:39], v[126:127]
	v_pk_add_f32 v[122:123], v[122:123], v[124:125]
	v_mul_f32_e32 v142, v135, v135
	v_mul_f32_e32 v106, v76, v76
	v_mul_f32_e32 v108, v77, v77
	v_pk_mul_f32 v[124:125], v[74:75], v[136:137]
	v_mov_b32_e32 v75, v135
	v_pk_fma_f32 v[134:135], v[78:79], v[78:79], v[128:129] op_sel_hi:[1,1,0]
	v_pk_fma_f32 v[130:131], v[80:81], v[80:81], v[130:131] op_sel_hi:[1,1,0]
	v_lshlrev_b32_e32 v139, 16, v93
	v_lshlrev_b32_e32 v138, 16, v92
	v_lshlrev_b32_e32 v92, 16, v99
	v_and_b32_e32 v93, 0xffff0000, v99
	v_pk_mul_f32 v[132:133], v[82:83], v[82:83]
	v_and_b32_e32 v95, 0xffff0000, v96
	v_and_b32_e32 v99, 0xffff0000, v97
	v_mul_f32_e32 v140, v117, v117
	v_mul_f32_e32 v128, v94, v94
	v_mul_f32_e32 v136, v98, v98
	v_lshlrev_b32_e32 v96, 16, v100
	v_and_b32_e32 v97, 0xffff0000, v100
	v_lshlrev_b32_e32 v100, 16, v101
	v_lshlrev_b32_e32 v145, 16, v103
	v_lshlrev_b32_e32 v144, 16, v102
	v_and_b32_e32 v103, 0xffff0000, v103
	v_and_b32_e32 v102, 0xffff0000, v102
	v_mov_b32_e32 v127, v91
	v_pk_add_f32 v[146:147], v[106:107], v[108:109]
	v_pk_add_f32 v[106:107], v[134:135], v[130:131]
	v_mov_b32_e32 v104, v138
	v_mov_b32_e32 v105, v82
	v_mov_b32_e32 v82, v139
	v_mov_b32_e32 v39, v117
	v_pk_fma_f32 v[132:133], v[138:139], v[138:139], v[132:133]
	v_mov_b32_e32 v138, v90
	v_and_b32_e32 v101, 0xffff0000, v101
	v_mov_b32_e32 v125, v129
	v_pk_fma_f32 v[128:129], v[94:95], v[94:95], v[128:129] op_sel_hi:[1,1,0]
	v_pk_fma_f32 v[136:137], v[98:99], v[98:99], v[136:137] op_sel_hi:[1,1,0]
	v_mov_b32_e32 v91, v135
	v_mov_b32_e32 v139, v131
	v_lshlrev_b32_e32 v106, 16, v120
	v_and_b32_e32 v117, 0xffff0000, v120
	v_mul_f32_e32 v120, v96, v96
	v_mul_f32_e32 v130, v100, v100
	v_pk_mul_f32 v[134:135], v[102:103], v[102:103]
	v_lshlrev_b32_e32 v148, 16, v118
	v_and_b32_e32 v149, 0xffff0000, v118
	v_lshlrev_b32_e32 v150, 16, v119
	v_and_b32_e32 v151, 0xffff0000, v119
	v_pk_add_f32 v[118:119], v[126:127], v[140:141]
	v_pk_add_f32 v[132:133], v[132:133], v[132:133] op_sel_hi:[0,1]
	v_lshlrev_b32_e32 v108, 16, v121
	v_and_b32_e32 v109, 0xffff0000, v121
	v_pk_add_f32 v[124:125], v[124:125], v[142:143]
	v_mul_f32_e32 v128, v92, v92
	v_mul_f32_e32 v136, v93, v93
	v_pk_mul_f32 v[126:127], v[90:91], v[138:139]
	v_pk_fma_f32 v[120:121], v[96:97], v[96:97], v[120:121] op_sel_hi:[1,1,0]
	v_pk_fma_f32 v[130:131], v[100:101], v[100:101], v[130:131] op_sel_hi:[1,1,0]
	v_pk_fma_f32 v[134:135], v[144:145], v[144:145], v[134:135]
	v_pk_add_f32 v[118:119], v[118:119], v[122:123]
	v_mul_f32_e32 v132, v154, v154
	v_mul_f32_e32 v138, v148, v148
	v_mul_f32_e32 v140, v150, v150
	v_mov_b32_e32 v142, v106
	v_pk_add_f32 v[122:123], v[124:125], v[146:147]
	v_mov_b32_e32 v127, v107
	v_pk_add_f32 v[124:125], v[128:129], v[136:137]
	v_pk_add_f32 v[128:129], v[134:135], v[134:135] op_sel_hi:[0,1]
	v_mov_b32_e32 v107, v121
	v_mov_b32_e32 v143, v131
	v_pk_add_f32 v[120:121], v[120:121], v[130:131]
	v_add_f32_e32 v130, v118, v119
	v_pk_fma_f32 v[134:135], v[148:149], v[148:149], v[138:139] op_sel_hi:[1,1,0]
	v_pk_fma_f32 v[136:137], v[150:151], v[150:151], v[140:141] op_sel_hi:[1,1,0]
	v_add_f32_e32 v131, v122, v123
	v_pk_add_f32 v[118:119], v[126:127], v[132:133]
	v_mul_f32_e32 v128, v117, v117
	v_pk_mul_f32 v[122:123], v[106:107], v[142:143]
	v_mov_b32_e32 v107, v117
	ds_bpermute_b32 v117, v110, v130
	v_mul_f32_e32 v134, v108, v108
	v_mul_f32_e32 v136, v109, v109
	ds_bpermute_b32 v126, v110, v131
	v_pk_add_f32 v[118:119], v[118:119], v[124:125]
	v_mov_b32_e32 v123, v121
	v_pk_add_f32 v[120:121], v[134:135], v[136:137]
	v_add_f32_e32 v124, v118, v119
	v_pk_add_f32 v[118:119], v[122:123], v[128:129]
	ds_bpermute_b32 v122, v110, v124
	v_pk_add_f32 v[118:119], v[118:119], v[120:121]
	s_waitcnt lgkmcnt(2)
; __device__ __forceinline__ float shfl_x(float v, int m, int lane) { return __builtin_bit_cast(float, __builtin_amdgcn_ds_bpermute((lane ^ m) << 2, __builtin_bit_cast(int, v))); }
; __device__ __forceinline__ float wave_sum(float v, int lane) {
; #pragma unroll
;     for (int o = 1; o < 64; o <<= 1) v += shfl_x(v, o, lane);
;     return v;
; __device__ __forceinline__ void final_norm_pass(const bf16_t* x16, float* out, const float* nw, int vcu, int ngw, const int wave_s) {
;     ...
;             float s = 0.f;
; #pragma unroll
;             for (int j = 0; j < 4; ++j) s += (v[j].x * v[j].x + v[j].y * v[j].y) + (v[j].z * v[j].z + v[j].w * v[j].w);
;             const float rstd = 1.0f / sqrtf(wave_sum(s, lane) * (1.0f / DM) + EPS);
;             f32x4* orow = (f32x4*)(out + (size_t)(m0 + i) * DM + 16 * lane);
; #pragma unroll
;             for (int j = 0; j < 4; ++j) orow[j] = v[j] * rstd * wv[j];
	v_add_f32_e32 v117, v130, v117
	v_add_f32_e32 v118, v118, v119
	ds_bpermute_b32 v119, v110, v118
	s_waitcnt lgkmcnt(2)
	v_add_f32_e32 v120, v131, v126
	ds_bpermute_b32 v121, v111, v117
	ds_bpermute_b32 v123, v111, v120
	s_waitcnt lgkmcnt(3)
	v_add_f32_e32 v122, v124, v122
	ds_bpermute_b32 v124, v111, v122
	s_waitcnt lgkmcnt(3)
	v_add_f32_e32 v118, v118, v119
	ds_bpermute_b32 v119, v111, v118
	s_waitcnt lgkmcnt(3)
	v_add_f32_e32 v117, v117, v121
	s_waitcnt lgkmcnt(2)
	v_add_f32_e32 v120, v120, v123
	ds_bpermute_b32 v121, v112, v117
	ds_bpermute_b32 v123, v112, v120
	v_addc_co_u32_e64 v29, s[0:1], -1, v19, s[0:1]
	s_waitcnt lgkmcnt(3)
	v_add_f32_e32 v122, v122, v124
	v_add_co_u32_e64 v30, s[0:1], s24, v18
	ds_bpermute_b32 v124, v112, v122
	s_nop 0
	v_addc_co_u32_e64 v31, s[0:1], -1, v19, s[0:1]
	s_waitcnt lgkmcnt(3)
	v_add_f32_e32 v118, v118, v119
	v_add_co_u32_e64 v32, s[0:1], s25, v18
	ds_bpermute_b32 v119, v112, v118
	s_waitcnt lgkmcnt(3)
	v_add_f32_e32 v117, v117, v121
	v_addc_co_u32_e64 v33, s[0:1], -1, v19, s[0:1]
	s_waitcnt lgkmcnt(2)
	v_add_f32_e32 v120, v120, v123
	ds_bpermute_b32 v121, v113, v117
	v_add_co_u32_e64 v34, s[0:1], s26, v18
	ds_bpermute_b32 v123, v113, v120
	s_nop 0
	v_addc_co_u32_e64 v35, s[0:1], -1, v19, s[0:1]
	s_waitcnt lgkmcnt(3)
	v_add_f32_e32 v122, v122, v124
	v_add_co_u32_e64 v36, s[0:1], s27, v18
	ds_bpermute_b32 v124, v113, v122
	s_nop 0
	v_addc_co_u32_e64 v37, s[0:1], -1, v19, s[0:1]
	s_waitcnt lgkmcnt(3)
	v_add_f32_e32 v118, v118, v119
	v_add_co_u32_e64 v42, s[0:1], s28, v18
	ds_bpermute_b32 v119, v113, v118
	s_waitcnt lgkmcnt(3)
	v_add_f32_e32 v117, v117, v121
	v_addc_co_u32_e64 v43, s[0:1], -1, v19, s[0:1]
	s_waitcnt lgkmcnt(2)
	v_add_f32_e32 v120, v120, v123
	ds_bpermute_b32 v121, v114, v117
	v_add_co_u32_e64 v44, s[0:1], s29, v18
	ds_bpermute_b32 v123, v114, v120
	s_nop 0
	v_addc_co_u32_e64 v45, s[0:1], -1, v19, s[0:1]
	s_waitcnt lgkmcnt(3)
	v_add_f32_e32 v122, v122, v124
	v_add_co_u32_e64 v46, s[0:1], s11, v18
	ds_bpermute_b32 v124, v114, v122
	s_nop 0
	v_addc_co_u32_e64 v47, s[0:1], -1, v19, s[0:1]
	s_waitcnt lgkmcnt(3)
	v_add_f32_e32 v118, v118, v119
	v_add_co_u32_e64 v48, s[0:1], s18, v18
	ds_bpermute_b32 v119, v114, v118
	s_waitcnt lgkmcnt(3)
	v_add_f32_e32 v117, v117, v121
	v_addc_co_u32_e64 v49, s[0:1], -1, v19, s[0:1]
	s_waitcnt lgkmcnt(2)
	v_add_f32_e32 v120, v120, v123
	ds_bpermute_b32 v121, v115, v117
	v_add_co_u32_e64 v50, s[0:1], s30, v18
	ds_bpermute_b32 v123, v115, v120
	s_nop 0
	v_addc_co_u32_e64 v51, s[0:1], -1, v19, s[0:1]
	s_waitcnt lgkmcnt(3)
	v_add_f32_e32 v122, v122, v124
	v_add_co_u32_e64 v52, s[0:1], s31, v18
	ds_bpermute_b32 v124, v115, v122
	s_nop 0
	v_addc_co_u32_e64 v53, s[0:1], -1, v19, s[0:1]
	s_waitcnt lgkmcnt(3)
	v_add_f32_e32 v118, v118, v119
	v_add_co_u32_e64 v54, s[0:1], s34, v18
	ds_bpermute_b32 v119, v115, v118
	s_waitcnt lgkmcnt(3)
	v_add_f32_e32 v117, v117, v121
	v_addc_co_u32_e64 v55, s[0:1], -1, v19, s[0:1]
	s_waitcnt lgkmcnt(2)
	v_add_f32_e32 v120, v120, v123
	v_fmamk_f32 v117, v117, 0x3a800000, v17
	v_cmp_lt_i32_e64 s[0:1], s33, v16
	v_fmamk_f32 v120, v120, 0x3a800000, v17
	v_mul_f32_e32 v121, 0x4f800000, v117
	v_cmp_gt_f32_e32 vcc, s19, v117
	s_or_b64 s[16:17], s[0:1], s[16:17]
	v_mul_f32_e32 v123, 0x4f800000, v120
	s_waitcnt lgkmcnt(1)
	v_add_f32_e32 v122, v122, v124
	v_cndmask_b32_e32 v117, v117, v121, vcc
	v_cmp_gt_f32_e64 s[0:1], s19, v120
	v_fmamk_f32 v121, v122, 0x3a800000, v17
	v_sqrt_f32_e32 v122, v117
	v_cndmask_b32_e64 v120, v120, v123, s[0:1]
	v_sqrt_f32_e32 v123, v120
	v_mul_f32_e32 v124, 0x4f800000, v121
	s_waitcnt lgkmcnt(0)
	v_add_f32_e32 v118, v118, v119
	v_cmp_gt_f32_e64 s[2:3], s19, v121
	v_fmamk_f32 v118, v118, 0x3a800000, v17
	v_cmp_gt_f32_e64 s[4:5], s19, v118
	v_cndmask_b32_e64 v119, v121, v124, s[2:3]
	v_sqrt_f32_e32 v121, v119
	v_mul_f32_e32 v124, 0x4f800000, v118
	v_cndmask_b32_e64 v118, v118, v124, s[4:5]
	v_add_u32_e32 v124, -1, v122
	v_add_u32_e32 v125, 1, v122
	v_add_u32_e32 v126, -1, v123
	v_fma_f32 v129, -v124, v122, v117
	v_add_u32_e32 v127, 1, v123
	v_sqrt_f32_e32 v128, v118
	v_fma_f32 v130, -v125, v122, v117
	v_fma_f32 v131, -v126, v123, v120
	v_cmp_ge_f32_e64 s[6:7], 0, v129
	v_fma_f32 v132, -v127, v123, v120
	v_cmp_ge_f32_e64 s[8:9], 0, v131
	v_cndmask_b32_e64 v122, v122, v124, s[6:7]
	v_cmp_lt_f32_e64 s[6:7], 0, v130
	v_add_u32_e32 v124, -1, v121
	v_cndmask_b32_e64 v123, v123, v126, s[8:9]
	v_add_u32_e32 v126, 1, v121
	v_cndmask_b32_e64 v122, v122, v125, s[6:7]
	v_cmp_lt_f32_e64 s[6:7], 0, v132
	v_fma_f32 v125, -v124, v121, v119
	v_mul_f32_e32 v129, 0x37800000, v122
	v_cndmask_b32_e64 v123, v123, v127, s[6:7]
	v_fma_f32 v127, -v126, v121, v119
	v_cmp_ge_f32_e64 s[6:7], 0, v125
	v_mul_f32_e32 v130, 0x37800000, v123
	v_cndmask_b32_e32 v122, v122, v129, vcc
	v_cndmask_b32_e64 v121, v121, v124, s[6:7]
	v_cmp_lt_f32_e64 s[6:7], 0, v127
	v_add_u32_e32 v124, -1, v128
	v_cmp_class_f32_e32 vcc, v117, v116
	v_add_u32_e32 v125, 1, v128
	v_cndmask_b32_e64 v123, v123, v130, s[0:1]
	v_cndmask_b32_e64 v121, v121, v126, s[6:7]
	v_fma_f32 v126, -v124, v128, v118
	v_cndmask_b32_e32 v117, v122, v117, vcc
	v_cmp_class_f32_e32 vcc, v120, v116
	v_fma_f32 v127, -v125, v128, v118
	v_mul_f32_e32 v122, 0x37800000, v121
	v_cndmask_b32_e32 v120, v123, v120, vcc
	v_cmp_ge_f32_e32 vcc, 0, v126
	v_cndmask_b32_e64 v121, v121, v122, s[2:3]
	v_cmp_class_f32_e64 s[2:3], v119, v116
	v_cndmask_b32_e32 v123, v128, v124, vcc
	v_cmp_lt_f32_e32 vcc, 0, v127
	v_div_scale_f32 v124, s[0:1], v117, v117, 1.0
	v_div_scale_f32 v127, s[6:7], v120, v120, 1.0
	v_cndmask_b32_e32 v122, v123, v125, vcc
	v_rcp_f32_e32 v125, v124
	v_rcp_f32_e32 v123, v127
; __device__ __forceinline__ void final_norm_pass(const bf16_t* x16, float* out, const float* nw, int vcu, int ngw, const int wave_s) {
;     ...
;             const float rstd = 1.0f / sqrtf(wave_sum(s, lane) * (1.0f / DM) + EPS);
;             f32x4* orow = (f32x4*)(out + (size_t)(m0 + i) * DM + 16 * lane);
; #pragma unroll
;             for (int j = 0; j < 4; ++j) orow[j] = v[j] * rstd * wv[j];
;         }
	v_cndmask_b32_e64 v129, v121, v119, s[2:3]
	v_mul_f32_e32 v119, 0x37800000, v122
	v_div_scale_f32 v121, s[2:3], v129, v129, 1.0
	v_cndmask_b32_e64 v119, v122, v119, s[4:5]
	v_cmp_class_f32_e32 vcc, v118, v116
	v_rcp_f32_e32 v131, v121
	v_div_scale_f32 v126, s[0:1], 1.0, v117, 1.0
	v_cndmask_b32_e32 v132, v119, v118, vcc
	v_div_scale_f32 v133, s[4:5], v132, v132, 1.0
	v_fma_f32 v118, -v124, v125, 1.0
	v_fma_f32 v119, -v127, v123, 1.0
	v_rcp_f32_e32 v135, v133
	v_div_scale_f32 v128, s[6:7], 1.0, v120, 1.0
	v_fmac_f32_e32 v125, v118, v125
	v_fmac_f32_e32 v123, v119, v123
	v_mul_f32_e32 v136, v126, v125
	v_mul_f32_e32 v118, v128, v123
	v_fma_f32 v119, -v121, v131, 1.0
	v_div_scale_f32 v130, s[2:3], 1.0, v129, 1.0
	v_fma_f32 v122, -v124, v136, v126
	v_fma_f32 v137, -v127, v118, v128
	v_fmac_f32_e32 v131, v119, v131
	v_fmac_f32_e32 v136, v122, v125
	v_fmac_f32_e32 v118, v137, v123
	v_mul_f32_e32 v119, v130, v131
	v_fma_f32 v122, -v133, v135, 1.0
	v_div_scale_f32 v134, s[4:5], 1.0, v132, 1.0
	v_fma_f32 v124, -v124, v136, v126
	v_fma_f32 v126, -v127, v118, v128
	v_fma_f32 v127, -v121, v119, v130
	v_fmac_f32_e32 v135, v122, v135
	s_mov_b64 vcc, s[6:7]
	v_div_fmas_f32 v118, v126, v123, v118
	v_fmac_f32_e32 v119, v127, v131
	v_mul_f32_e32 v126, v134, v135
	v_div_fixup_f32 v118, v118, v120, 1.0
	v_fma_f32 v120, -v121, v119, v130
	v_fma_f32 v121, -v133, v126, v134
	s_mov_b64 vcc, s[2:3]
	v_pk_mul_f32 v[68:69], v[118:119], v[68:69] op_sel_hi:[0,1]
	v_pk_mul_f32 v[70:71], v[118:119], v[70:71] op_sel_hi:[0,1]
	v_pk_mul_f32 v[88:89], v[118:119], v[88:89] op_sel_hi:[0,1]
	v_pk_mul_f32 v[72:73], v[118:119], v[72:73] op_sel_hi:[0,1]
	v_pk_mul_f32 v[76:77], v[76:77], v[118:119] op_sel_hi:[1,0]
	v_div_fmas_f32 v127, v120, v131, v119
	v_fmac_f32_e32 v126, v121, v135
	v_mov_b32_e32 v91, v154
	v_pk_mul_f32 v[84:85], v[118:119], v[84:85] op_sel_hi:[0,1]
	v_pk_mul_f32 v[86:87], v[118:119], v[86:87] op_sel_hi:[0,1]
	v_pk_mul_f32 v[122:123], v[74:75], v[118:119] op_sel_hi:[1,0]
	v_pk_mul_f32 v[70:71], v[14:15], v[70:71]
	v_pk_mul_f32 v[68:69], v[12:13], v[68:69]
	v_pk_mul_f32 v[74:75], v[10:11], v[72:73]
	v_pk_mul_f32 v[72:73], v[8:9], v[88:89]
	v_pk_mul_f32 v[120:121], v[2:3], v[76:77]
	v_div_fixup_f32 v76, v127, v129, 1.0
	v_fma_f32 v77, -v133, v126, v134
	s_mov_b64 vcc, s[4:5]
	v_pk_mul_f32 v[86:87], v[6:7], v[86:87]
	v_pk_mul_f32 v[84:85], v[4:5], v[84:85]
	v_pk_mul_f32 v[118:119], v[0:1], v[122:123]
	global_store_dwordx4 v[22:23], v[68:71], off
	global_store_dwordx4 v[24:25], v[72:75], off
	global_store_dwordx4 v[26:27], v[84:87], off
	global_store_dwordx4 v[28:29], v[118:121], off
	v_pk_mul_f32 v[22:23], v[76:77], v[78:79] op_sel_hi:[0,1]
	v_pk_mul_f32 v[24:25], v[76:77], v[80:81] op_sel_hi:[0,1]
	v_pk_mul_f32 v[26:27], v[76:77], v[104:105] op_sel_hi:[0,1]
	v_pk_mul_f32 v[28:29], v[76:77], v[82:83] op_sel_hi:[0,1]
	v_pk_mul_f32 v[68:69], v[76:77], v[94:95] op_sel_hi:[0,1]
	v_pk_mul_f32 v[70:71], v[76:77], v[98:99] op_sel_hi:[0,1]
	v_pk_mul_f32 v[72:73], v[90:91], v[76:77] op_sel_hi:[1,0]
	v_pk_mul_f32 v[74:75], v[92:93], v[76:77] op_sel_hi:[1,0]
	v_div_fmas_f32 v76, v77, v135, v126
	s_mov_b64 vcc, s[0:1]
	v_pk_mul_f32 v[24:25], v[14:15], v[24:25]
	v_pk_mul_f32 v[22:23], v[12:13], v[22:23]
	v_pk_mul_f32 v[68:69], v[4:5], v[68:69]
	v_div_fixup_f32 v76, v76, v132, 1.0
	v_div_fmas_f32 v77, v124, v125, v136
	v_mov_b32_e32 v152, v144
	v_mov_b32_e32 v153, v102
	v_mov_b32_e32 v102, v145
	v_pk_mul_f32 v[28:29], v[10:11], v[28:29]
	v_pk_mul_f32 v[26:27], v[8:9], v[26:27]
	v_pk_mul_f32 v[70:71], v[6:7], v[70:71]
	v_pk_mul_f32 v[74:75], v[2:3], v[74:75]
	v_pk_mul_f32 v[72:73], v[0:1], v[72:73]
	global_store_dwordx4 v[30:31], v[22:25], off
	global_store_dwordx4 v[32:33], v[26:29], off
	global_store_dwordx4 v[34:35], v[68:71], off
	global_store_dwordx4 v[36:37], v[72:75], off
	v_pk_mul_f32 v[22:23], v[76:77], v[96:97] op_sel_hi:[0,1]
	v_pk_mul_f32 v[24:25], v[76:77], v[100:101] op_sel_hi:[0,1]
	v_div_fixup_f32 v68, v77, v117, 1.0
	v_pk_mul_f32 v[26:27], v[76:77], v[152:153] op_sel_hi:[0,1]
	v_pk_mul_f32 v[28:29], v[76:77], v[102:103] op_sel_hi:[0,1]
	v_pk_mul_f32 v[30:31], v[76:77], v[148:149] op_sel_hi:[0,1]
	v_pk_mul_f32 v[32:33], v[76:77], v[150:151] op_sel_hi:[0,1]
	v_pk_mul_f32 v[34:35], v[106:107], v[76:77] op_sel_hi:[1,0]
	v_pk_mul_f32 v[36:37], v[108:109], v[76:77] op_sel_hi:[1,0]
	v_pk_mul_f32 v[24:25], v[14:15], v[24:25]
	v_pk_mul_f32 v[22:23], v[12:13], v[22:23]
	v_pk_mul_f32 v[56:57], v[68:69], v[56:57] op_sel_hi:[0,1]
	v_pk_mul_f32 v[58:59], v[68:69], v[58:59] op_sel_hi:[0,1]
	v_pk_mul_f32 v[28:29], v[10:11], v[28:29]
	v_pk_mul_f32 v[26:27], v[8:9], v[26:27]
	v_pk_mul_f32 v[32:33], v[6:7], v[32:33]
	v_pk_mul_f32 v[30:31], v[4:5], v[30:31]
	v_pk_mul_f32 v[36:37], v[2:3], v[36:37]
	v_pk_mul_f32 v[34:35], v[0:1], v[34:35]
	v_pk_mul_f32 v[66:67], v[68:69], v[66:67] op_sel_hi:[0,1]
	v_pk_mul_f32 v[60:61], v[68:69], v[60:61] op_sel_hi:[0,1]
	v_pk_mul_f32 v[62:63], v[68:69], v[62:63] op_sel_hi:[0,1]
	v_pk_mul_f32 v[64:65], v[68:69], v[64:65] op_sel_hi:[0,1]
	v_pk_mul_f32 v[38:39], v[38:39], v[68:69] op_sel_hi:[1,0]
	v_pk_mul_f32 v[40:41], v[40:41], v[68:69] op_sel_hi:[1,0]
	global_store_dwordx4 v[42:43], v[22:25], off
	global_store_dwordx4 v[44:45], v[26:29], off
	global_store_dwordx4 v[46:47], v[30:33], off
	global_store_dwordx4 v[48:49], v[34:37], off
	v_pk_mul_f32 v[24:25], v[14:15], v[58:59]
	v_pk_mul_f32 v[22:23], v[12:13], v[56:57]
	v_pk_mul_f32 v[28:29], v[10:11], v[60:61]
	v_pk_mul_f32 v[26:27], v[8:9], v[66:67]
	v_pk_mul_f32 v[32:33], v[6:7], v[64:65]
	v_pk_mul_f32 v[30:31], v[4:5], v[62:63]
	v_pk_mul_f32 v[36:37], v[2:3], v[40:41]
	v_pk_mul_f32 v[34:35], v[0:1], v[38:39]
	global_store_dwordx4 v[50:51], v[22:25], off
	global_store_dwordx4 v[52:53], v[26:29], off
	global_store_dwordx4 v[54:55], v[30:33], off
	global_store_dwordx4 v[18:19], v[34:37], off
	v_lshl_add_u64 v[18:19], v[18:19], 0, s[12:13]
	s_andn2_b64 exec, exec, s[16:17]
	s_cbranch_execnz .LBB0_1353
